# low-rank gate GEMM inner loop: 20 loads per K step issued together (were serialized load/wait/MFMA)
# speedup vs baseline: 1.0255x; 1.0051x over previous
; DI int opaque_bid() { int b = blockIdx.x; asm volatile("" : "+s"(b)); return b; }
; DI int opaque_gdim() { int g = gridDim.x; asm volatile("" : "+s"(g)); return g; }
; DI int opaque_tid(int wid0) { int w = wid0; asm volatile("" : "+s"(w)); return w * 64 + hw_lane(); }
; #define MFMA16(a, b, c) __builtin_amdgcn_mfma_f32_16x16x32_bf16((a), (b), (c), 0, 0, 0)
; DI void glr_gemm(int wid0, const bf16_t* hn, const bf16_t* WgT, float* glr) {
;     const int tid_ = opaque_tid(wid0), lane = tid_ & 63, wave = tid_ >> 6, nw = opaque_gdim() * 8;
;     const int gw = ((7 - wave) * opaque_gdim() + opaque_bid());
;     for (int t = gw; t < RCONT / 64; t += nw) {
;         const bf16_t* ap = hn + (size_t)(t * 64 + (lane & 15)) * 1024 + 8 * (lane >> 4);
;         const bf16_t* bp = WgT + (size_t)(lane & 15) * 1024 + 8 * (lane >> 4);
;         f32x4 acc[4];
; #pragma unroll
;         for (int c = 0; c < 4; ++c) acc[c] = (f32x4){0.f, 0.f, 0.f, 0.f};
; #pragma unroll 4
;         for (int k0 = 0; k0 < 1024; k0 += 32) {
;             const bf16x8 b = *(const bf16x8*)(bp + k0);
; #pragma unroll
;             for (int c = 0; c < 4; ++c) { const bf16x8 a = *(const bf16x8*)(ap + (size_t)c * 16 * 1024 + k0); acc[c] = MFMA16(b, a, acc[c]); }
;         }
; #pragma unroll
;         for (int c = 0; c < 4; ++c) *(f32x4*)(glr + (size_t)(t * 64 + c * 16 + (lane & 15)) * 16 + 4 * (lane >> 4)) = acc[c];
;     }
.LBB0_486:
	v_lshl_add_u64 v[30:31], v[26:27], 0, v[0:1]
	s_mov_b32 s8, 0x1440000
	v_add_co_u32_e32 v38, vcc, s8, v30
	v_lshl_add_u64 v[40:41], v[24:25], 0, v[0:1]
	s_nop 0
	v_addc_co_u32_e32 v39, vcc, 0, v31, vcc
	global_load_dwordx4 v[92:95], v[38:39], off
	s_mov_b32 s8, 0x1448000
	v_add_co_u32_e32 v42, vcc, s8, v40
	s_mov_b32 s8, 0x1450000
	s_nop 0
	v_addc_co_u32_e32 v43, vcc, 0, v41, vcc
	global_load_dwordx4 v[96:99], v[42:43], off
	v_add_co_u32_e32 v44, vcc, s8, v40
	s_mov_b32 s8, 0x1458000
	s_nop 0
	v_addc_co_u32_e32 v45, vcc, 0, v41, vcc
	v_add_co_u32_e32 v46, vcc, s8, v40
	s_mov_b32 s8, 0x1460000
	s_nop 0
	v_addc_co_u32_e32 v47, vcc, 0, v41, vcc
	v_add_co_u32_e32 v40, vcc, s8, v40
	s_addk_i32 s7, 0x80
	s_nop 0
	v_addc_co_u32_e32 v41, vcc, 0, v41, vcc
	v_lshl_add_u64 v[26:27], v[26:27], 0, s[34:35]
	v_lshl_add_u64 v[24:25], v[24:25], 0, s[34:35]
	s_cmpk_gt_u32 s7, 0x3df
	global_load_dwordx4 v[100:103], v[44:45], off
	global_load_dwordx4 v[104:107], v[46:47], off
	global_load_dwordx4 v[108:111], v[40:41], off
	global_load_dwordx4 v[112:115], v[38:39], off offset:64
	global_load_dwordx4 v[116:119], v[42:43], off offset:64
	global_load_dwordx4 v[120:123], v[44:45], off offset:64
	global_load_dwordx4 v[124:127], v[46:47], off offset:64
	global_load_dwordx4 v[128:131], v[40:41], off offset:64
	global_load_dwordx4 v[132:135], v[38:39], off offset:128
	global_load_dwordx4 v[136:139], v[42:43], off offset:128
	global_load_dwordx4 v[140:143], v[44:45], off offset:128
	global_load_dwordx4 v[144:147], v[46:47], off offset:128
	global_load_dwordx4 v[148:151], v[40:41], off offset:128
	global_load_dwordx4 v[152:155], v[38:39], off offset:192
	global_load_dwordx4 v[156:159], v[42:43], off offset:192
	global_load_dwordx4 v[160:163], v[44:45], off offset:192
	global_load_dwordx4 v[176:179], v[46:47], off offset:192
	global_load_dwordx4 v[180:183], v[40:41], off offset:192
	s_waitcnt vmcnt(18)
	v_mfma_f32_16x16x32_bf16 v[14:17], v[92:95], v[96:99], v[14:17]
	s_waitcnt vmcnt(17)
	v_mfma_f32_16x16x32_bf16 v[10:13], v[92:95], v[100:103], v[10:13]
	s_waitcnt vmcnt(16)
	v_mfma_f32_16x16x32_bf16 v[6:9], v[92:95], v[104:107], v[6:9]
	s_waitcnt vmcnt(15)
	v_mfma_f32_16x16x32_bf16 v[2:5], v[92:95], v[108:111], v[2:5]
	s_waitcnt vmcnt(13)
	v_mfma_f32_16x16x32_bf16 v[14:17], v[112:115], v[116:119], v[14:17]
	s_waitcnt vmcnt(12)
	v_mfma_f32_16x16x32_bf16 v[10:13], v[112:115], v[120:123], v[10:13]
	s_waitcnt vmcnt(11)
	v_mfma_f32_16x16x32_bf16 v[6:9], v[112:115], v[124:127], v[6:9]
	s_waitcnt vmcnt(10)
	v_mfma_f32_16x16x32_bf16 v[2:5], v[112:115], v[128:131], v[2:5]
	s_waitcnt vmcnt(8)
	v_mfma_f32_16x16x32_bf16 v[14:17], v[132:135], v[136:139], v[14:17]
	s_waitcnt vmcnt(7)
	v_mfma_f32_16x16x32_bf16 v[10:13], v[132:135], v[140:143], v[10:13]
	s_waitcnt vmcnt(6)
	v_mfma_f32_16x16x32_bf16 v[6:9], v[132:135], v[144:147], v[6:9]
	s_waitcnt vmcnt(5)
	v_mfma_f32_16x16x32_bf16 v[2:5], v[132:135], v[148:151], v[2:5]
	s_waitcnt vmcnt(3)
	v_mfma_f32_16x16x32_bf16 v[14:17], v[152:155], v[156:159], v[14:17]
	s_waitcnt vmcnt(2)
	v_mfma_f32_16x16x32_bf16 v[10:13], v[152:155], v[160:163], v[10:13]
	s_waitcnt vmcnt(1)
	v_mfma_f32_16x16x32_bf16 v[6:9], v[152:155], v[176:179], v[6:9]
	s_waitcnt vmcnt(0)
	v_mfma_f32_16x16x32_bf16 v[2:5], v[152:155], v[180:183], v[2:5]
	s_cbranch_scc0 .LBB0_486
	v_lshl_or_b32 v24, v28, 6, v29
	v_ashrrev_i32_e32 v25, 31, v24
	v_lshlrev_b64 v[26:27], 6, v[24:25]
	v_lshl_add_u64 v[26:27], v[18:19], 0, v[26:27]
	global_store_dwordx4 v[26:27], v[14:17], off
	v_add_u32_e32 v28, s2, v28
	s_movk_i32 s7, 0x200
	v_or_b32_e32 v14, 16, v24
	v_ashrrev_i32_e32 v15, 31, v14
	v_lshlrev_b64 v[14:15], 6, v[14:15]
	v_lshl_add_u64 v[14:15], v[18:19], 0, v[14:15]
	global_store_dwordx4 v[14:15], v[10:13], off
	v_cmp_lt_i32_e32 vcc, s7, v28
	s_or_b64 s[4:5], vcc, s[4:5]
	v_or_b32_e32 v10, 32, v24
	v_ashrrev_i32_e32 v11, 31, v10
	v_lshlrev_b64 v[10:11], 6, v[10:11]
	v_lshl_add_u64 v[10:11], v[18:19], 0, v[10:11]
	global_store_dwordx4 v[10:11], v[6:9], off
	v_add_u32_e32 v22, s6, v22
	s_nop 0
	v_or_b32_e32 v6, 48, v24
	v_ashrrev_i32_e32 v7, 31, v6
	v_lshlrev_b64 v[6:7], 6, v[6:7]
	v_lshl_add_u64 v[6:7], v[18:19], 0, v[6:7]
	global_store_dwordx4 v[6:7], v[2:5], off
	s_andn2_b64 exec, exec, s[4:5]
	s_cbranch_execnz .LBB0_485
